# v24 + small start stagger also at the P3 and P5 GEMM entries (2-2.5 us windows)
# baseline (speedup 1.0000x reference)
.LBB0_249:
	s_load_dwordx2 s[2:3], s[82:83], 0x118
	s_waitcnt lgkmcnt(0)
	s_cmp_lt_i32 s2, 4
	s_cselect_b64 s[2:3], -1, 0
	s_and_b64 s[2:3], s[2:3], s[0:1]
	s_andn2_b64 vcc, exec, s[2:3]
	s_cbranch_vccnz .LBB0_298
	v_lshlrev_b32_e32 v2, 4, v0
	v_and_b32_e32 v1, 32, v0
	v_lshrrev_b32_e32 v3, 5, v0
	v_lshrrev_b32_e32 v5, 1, v0
	v_or_b32_e32 v174, 0x2000, v2
	v_bfe_u32 v173, v0, 2, 4
	v_bitop3_b32 v1, v2, v1, 48 bitop3:0x6c
	v_and_b32_e32 v3, 4, v3
	v_bfe_u32 v4, v0, 2, 2
	v_and_b32_e32 v130, 24, v5
	v_lshrrev_b32_e32 v2, 7, v174
	s_movk_i32 s1, 0x70
	v_or3_b32 v3, v3, v4, v130
	v_lshrrev_b32_e32 v4, 3, v0
	v_and_or_b32 v180, v2, s1, v173
	s_movk_i32 s1, 0x60
	v_and_or_b32 v179, v4, 32, v3
	v_and_or_b32 v181, v2, s1, v3
	v_lshlrev_b32_e32 v2, 6, v0
	v_lshlrev_b32_e32 v3, 2, v0
	v_and_b32_e32 v172, 64, v0
	v_lshlrev_b32_e32 v176, 1, v130
	v_and_b32_e32 v2, 0x3c0, v2
	v_and_b32_e32 v3, 32, v3
	v_readfirstlane_b32 s0, v0
	v_or_b32_e32 v131, v1, v172
	v_and_or_b32 v178, v4, 48, v173
	v_and_b32_e32 v175, 15, v0
	s_cmpk_gt_i32 s81, 0x2ff
	v_bitop3_b32 v177, v176, v3, v2 bitop3:0x36
	s_cbranch_scc1 .LBB0_274
	s_memrealtime s[98:99]
	s_and_b32 s100, s81, 0xff
	s_mulk_i32 s100, 0xc8
	s_lshr_b32 s100, s100, 8
	s_waitcnt lgkmcnt(0)
	s_add_u32 s100, s98, s100
.Lstg_p3:
	s_memrealtime s[98:99]
	s_waitcnt lgkmcnt(0)
	s_sub_u32 s101, s100, s98
	s_cmp_gt_i32 s101, 0
	s_cbranch_scc1 .Lstg_p3
	s_load_dwordx2 s[4:5], s[82:83], 0x90
	s_movk_i32 s7, 0x61
	v_mul_u32_u24_e32 v2, 0x300, v181
	v_lshrrev_b32_e32 v3, 1, v131
	v_or_b32_e32 v2, v2, v3
	s_waitcnt lgkmcnt(0)
	s_add_u32 s17, s4, 0x1ba00000
	s_addc_u32 s26, s5, 0
	s_add_u32 s27, s4, 0x2300000
	s_addc_u32 s28, s5, 0
	s_ashr_i32 s30, s81, 31
	s_lshr_b32 s5, s30, 29
	s_add_i32 s5, s81, s5
	s_lshr_b32 s4, s0, 6
	s_ashr_i32 s6, s5, 3
	s_and_b32 s5, s5, -8
	s_lshr_b32 s1, s0, 8
	s_lshl_b32 s29, s4, 10
	s_sub_i32 s5, s81, s5
	s_cmp_lt_i32 s5, 0
	s_cselect_b32 s7, s7, 0x60
	s_mul_i32 s5, s5, s7
	s_add_i32 s5, s5, s6
	s_mul_hi_i32 s6, s5, 0x2aaaaaab
	s_lshr_b32 s7, s6, 31
	s_ashr_i32 s6, s6, 3
	s_add_i32 s6, s6, s7
	s_lshl_b32 s7, s6, 3
	s_mul_i32 s6, s6, 48
	s_sub_i32 s6, s5, s6
	s_bfe_i32 s5, s6, 0x80000
	s_bfe_u32 s5, s5, 0x3000c
	s_add_i32 s8, s6, s5
	s_bfe_i32 s5, s8, 0x80000
	s_and_b32 s8, s8, 0xf8
	s_sext_i32_i16 s9, s5
	s_sub_i32 s6, s6, s8
	v_mul_u32_u24_e32 v10, 0x300, v180
	s_sext_i32_i8 s6, s6
	s_ashr_i32 s8, s9, 3
	v_lshlrev_b32_e32 v132, 1, v2
	v_or_b32_e32 v2, v10, v3
	s_lshr_b32 s5, s9, 3
	s_add_i32 s6, s7, s6
	s_mul_hi_i32 s9, s8, 0x60000
	s_mul_i32 s8, s8, 0x60000
	v_lshlrev_b32_e32 v134, 1, v2
	v_mul_u32_u24_e32 v2, 0x300, v179
	s_add_u32 s22, s27, s8
	v_or_b32_e32 v2, v2, v3
	s_addc_u32 s23, s28, s9
	s_add_i32 s31, s29, 0
	v_lshlrev_b32_e32 v136, 1, v2
	s_add_i32 m0, s31, 0x10000
	s_mul_i32 s10, s6, 0x60000
	global_load_lds_dwordx4 v136, s[22:23]
	s_add_i32 m0, s31, 0x12000
	s_add_u32 s8, s22, 0x30000
	global_load_lds_dwordx4 v132, s[22:23]
	s_addc_u32 s9, s23, 0
	s_add_i32 m0, s31, 0x14000
	v_mul_u32_u24_e32 v11, 0x300, v178
	global_load_lds_dwordx4 v136, s[8:9]
	s_add_i32 m0, s31, 0x16000
	s_mul_hi_i32 s7, s6, 0x60000
	s_add_u32 s20, s17, s10
	v_or_b32_e32 v2, v3, v11
	s_addc_u32 s21, s26, s7
	s_add_i32 s33, s31, 0x2000
	v_lshlrev_b32_e32 v138, 1, v2
	global_load_lds_dwordx4 v132, s[8:9]
	s_mov_b32 m0, s31
	s_add_u32 s8, s20, 0x30000
	global_load_lds_dwordx4 v138, s[20:21]
	s_mov_b32 m0, s33
	s_addc_u32 s9, s21, 0
	s_add_i32 s34, s31, 0x4000
	global_load_lds_dwordx4 v134, s[20:21]
	s_mov_b32 m0, s34
	s_add_i32 s35, s31, 0x6000
	global_load_lds_dwordx4 v138, s[8:9]
	s_mov_b32 m0, s35
	v_mov_b32_e32 v141, 0
	global_load_lds_dwordx4 v134, s[8:9]
	v_mov_b32_e32 v137, v141
	v_mov_b32_e32 v133, v141
	v_mov_b32_e32 v139, v141
	v_mov_b32_e32 v135, v141
	s_cmp_eq_u32 s1, 1
	s_mov_b32 s7, 0
	v_lshl_add_u64 v[8:9], s[22:23], 0, v[136:137]
	v_lshl_add_u64 v[6:7], s[22:23], 0, v[132:133]
	v_lshl_add_u64 v[2:3], s[20:21], 0, v[138:139]
	s_cselect_b64 s[8:9], -1, 0
	s_cmp_lg_u32 s1, 1
	v_lshl_add_u64 v[4:5], s[20:21], 0, v[134:135]
	s_cbranch_scc1 .LBB0_253
	s_barrier

.LBB0_513:
	v_readlane_b32 s2, v245, 5
	v_readlane_b32 s3, v245, 6
	s_cmp_lt_i32 s2, 6
	s_cselect_b64 s[2:3], -1, 0
	s_and_b64 s[0:1], s[2:3], s[0:1]
	s_andn2_b64 vcc, exec, s[0:1]
	s_cbranch_vccnz .LBB0_538
	s_cmpk_gt_i32 s81, 0x3ff
	v_readfirstlane_b32 s5, v0
	s_cbranch_scc1 .LBB0_538
	s_memrealtime s[98:99]
	s_and_b32 s100, s81, 0xff
	s_mulk_i32 s100, 0xfa
	s_lshr_b32 s100, s100, 8
	s_waitcnt lgkmcnt(0)
	s_add_u32 s100, s98, s100
.Lstg_p5:
	s_memrealtime s[98:99]
	s_waitcnt lgkmcnt(0)
	s_sub_u32 s101, s100, s98
	s_cmp_gt_i32 s101, 0
	s_cbranch_scc1 .Lstg_p5
	s_ashr_i32 s26, s81, 31
	s_lshr_b32 s0, s26, 29
	s_add_i32 s3, s81, s0
	s_and_b32 s0, s3, -8
	s_sub_i32 s4, s81, s0
	s_cmp_gt_i32 s4, -1
	s_cbranch_scc0 .LBB0_517
	s_lshl_b32 s2, s4, 7
	s_cbranch_execz .LBB0_518
	s_branch .LBB0_519
